# attn-B first-tile rescale branch unconditional on top of A-mask/B-trim stack
# baseline (speedup 1.0000x reference)
.LBB0_683:
	s_nop 6
	v_max_f32_e32 v46, v5, v5
	v_max_f32_e32 v47, v4, v4
	v_max_f32_e32 v46, v47, v46
	v_max3_f32 v46, v46, v6, v7
	v_max3_f32 v44, v20, v21, v22
	v_max3_f32 v46, v46, v8, v9
	v_max3_f32 v44, v44, v23, v24
	v_max3_f32 v46, v46, v10, v11
	v_max3_f32 v44, v44, v25, v26
	v_max3_f32 v46, v46, v12, v13
	v_max3_f32 v44, v44, v27, v28
	v_max3_f32 v46, v46, v14, v15
	v_mul_f32_e32 v166, s16, v247
	v_mul_f32_e32 v167, s16, v250
	v_max3_f32 v44, v44, v29, v30
	v_max3_f32 v46, v46, v16, v17
	v_cndmask_b32_e32 v45, v167, v166, vcc
	v_max3_f32 v44, v44, v31, v32
	v_max3_f32 v46, v46, v18, v19
	v_max3_f32 v44, v44, v33, v34
	v_add_f32_e32 v46, v45, v46
	v_max3_f32 v44, v44, v35, v46
	v_mov_b32_e32 v46, v44
	s_nop 1
	v_permlane32_swap_b32_e32 v44, v46
	v_max_f32_e32 v46, v46, v46
	v_max_f32_e32 v44, v44, v44
	s_and_b32 s17, s77, 0x3fffffc0
	v_mul_f32_e64 v2, v162, |v163|
	v_max_f32_e32 v44, v44, v46
	s_lshl_b32 s17, s17, 2
	v_fmac_f32_e32 v2, 0x3e38aa3b, v44
	s_add_i32 s26, s17, 0
	v_add_f32_e32 v44, 0x7149f2ca, v2
	s_add_i32 s26, s26, 0x21000
	v_cmp_ge_f32_e32 vcc, s79, v44
	s_cmp_eq_u64 vcc, exec
	v_max_f32_e32 v2, 0xf149f2ca, v2
	s_cselect_b64 vcc, -1, 0
	v_cndmask_b32_e32 v168, v2, v235, vcc
	v_sub_f32_e32 v44, 0xf149f2ca, v2
	v_fma_f32 v2, v162, |v163|, -v168
	v_fmamk_f32 v22, v22, 0x3e38aa3b, v2
	v_exp_f32_e32 v46, v22
	v_fmamk_f32 v22, v23, 0x3e38aa3b, v2
	v_exp_f32_e32 v47, v22
	v_fmamk_f32 v22, v24, 0x3e38aa3b, v2
	v_exp_f32_e32 v24, v22
	v_fmamk_f32 v22, v25, 0x3e38aa3b, v2
	v_exp_f32_e32 v25, v22
	v_fmamk_f32 v22, v26, 0x3e38aa3b, v2
	v_exp_f32_e32 v26, v22
	v_fmamk_f32 v22, v27, 0x3e38aa3b, v2
	v_exp_f32_e32 v27, v22
	v_fmamk_f32 v22, v28, 0x3e38aa3b, v2
	v_exp_f32_e32 v28, v22
	v_fmamk_f32 v22, v29, 0x3e38aa3b, v2
	v_exp_f32_e32 v29, v22
	v_fmamk_f32 v22, v30, 0x3e38aa3b, v2
	v_fmamk_f32 v20, v20, 0x3e38aa3b, v2
	v_exp_f32_e32 v30, v22
	v_fmamk_f32 v22, v31, 0x3e38aa3b, v2
	v_exp_f32_e32 v20, v20
	v_fmamk_f32 v21, v21, 0x3e38aa3b, v2
	v_exp_f32_e32 v31, v22
	v_fmamk_f32 v22, v32, 0x3e38aa3b, v2
	v_exp_f32_e32 v21, v21
	v_exp_f32_e32 v32, v22
	v_fmamk_f32 v22, v33, 0x3e38aa3b, v2
	v_exp_f32_e32 v33, v22
	v_fmamk_f32 v22, v34, 0x3e38aa3b, v2
	v_exp_f32_e32 v34, v22
	v_fmamk_f32 v22, v35, 0x3e38aa3b, v2
	v_fmac_f32_e32 v2, 0x3e38aa3b, v45
	v_fmamk_f32 v4, v4, 0x3e38aa3b, v2
	v_fmamk_f32 v5, v5, 0x3e38aa3b, v2
	v_fmamk_f32 v6, v6, 0x3e38aa3b, v2
	v_fmamk_f32 v7, v7, 0x3e38aa3b, v2
	v_fmamk_f32 v8, v8, 0x3e38aa3b, v2
	v_fmamk_f32 v9, v9, 0x3e38aa3b, v2
	v_fmamk_f32 v10, v10, 0x3e38aa3b, v2
	v_fmamk_f32 v11, v11, 0x3e38aa3b, v2
	v_fmamk_f32 v12, v12, 0x3e38aa3b, v2
	v_fmamk_f32 v13, v13, 0x3e38aa3b, v2
	v_fmamk_f32 v14, v14, 0x3e38aa3b, v2
	v_fmamk_f32 v15, v15, 0x3e38aa3b, v2
	v_fmamk_f32 v16, v16, 0x3e38aa3b, v2
	v_fmamk_f32 v17, v17, 0x3e38aa3b, v2
	v_fmamk_f32 v18, v18, 0x3e38aa3b, v2
	v_fmac_f32_e32 v2, 0x3e38aa3b, v19
	v_add_f32_e32 v19, 0, v20
	v_add_f32_e32 v19, v21, v19
	v_add_f32_e32 v19, v46, v19
	v_add_f32_e32 v19, v47, v19
	v_add_f32_e32 v19, v24, v19
	v_add_f32_e32 v19, v25, v19
	v_add_f32_e32 v19, v26, v19
	v_add_f32_e32 v19, v27, v19
	v_add_f32_e32 v19, v28, v19
	v_add_f32_e32 v19, v29, v19
	v_add_f32_e32 v19, v30, v19
	v_exp_f32_e32 v35, v22
	v_add_f32_e32 v19, v31, v19
	v_exp_f32_e32 v4, v4
	v_add_f32_e32 v19, v32, v19
	v_exp_f32_e32 v5, v5
	v_add_f32_e32 v19, v33, v19
	v_exp_f32_e32 v6, v6
	v_add_f32_e32 v19, v34, v19
	v_exp_f32_e32 v7, v7
	v_add_f32_e32 v19, v35, v19
	v_exp_f32_e32 v8, v8
	v_add_f32_e32 v19, v4, v19
	v_exp_f32_e32 v9, v9
	v_add_f32_e32 v19, v5, v19
	v_exp_f32_e32 v10, v10
	v_add_f32_e32 v19, v6, v19
	v_exp_f32_e32 v11, v11
	v_add_f32_e32 v19, v7, v19
	v_exp_f32_e32 v12, v12
	v_add_f32_e32 v19, v8, v19
	v_exp_f32_e32 v13, v13
	v_add_f32_e32 v19, v9, v19
	v_exp_f32_e32 v14, v14
	v_add_f32_e32 v19, v10, v19
	v_exp_f32_e32 v15, v15
	v_add_f32_e32 v19, v11, v19
	v_exp_f32_e32 v16, v16
	v_add_f32_e32 v19, v12, v19
	v_exp_f32_e32 v17, v17
	v_add_f32_e32 v19, v13, v19
	v_exp_f32_e32 v18, v18
	v_add_f32_e32 v19, v14, v19
	v_exp_f32_e32 v2, v2
	v_add_f32_e32 v19, v15, v19
	v_exp_f32_e32 v44, v44
	v_add_f32_e32 v19, v16, v19
	v_add_f32_e32 v19, v17, v19
	v_add_f32_e32 v19, v18, v19
	v_add_f32_e32 v22, v2, v19
	v_cndmask_b32_e64 v44, v44, 1.0, vcc
	v_mov_b32_e32 v23, v22
	s_nop 1
	v_permlane32_swap_b32_e32 v22, v23
	v_cmp_gt_f32_e32 vcc, 1.0, v44
	v_cvt_pk_bf16_f32 v134, v20, v21
	v_cvt_pk_bf16_f32 v135, v46, v47
	v_cvt_pk_bf16_f32 v136, v24, v25
	v_cvt_pk_bf16_f32 v137, v26, v27
	v_cvt_pk_bf16_f32 v130, v28, v29
	v_cvt_pk_bf16_f32 v131, v30, v31
	v_cvt_pk_bf16_f32 v132, v32, v33
	v_cvt_pk_bf16_f32 v133, v34, v35
	v_cvt_pk_bf16_f32 v126, v4, v5
	v_cvt_pk_bf16_f32 v127, v6, v7
	v_cvt_pk_bf16_f32 v128, v8, v9
	v_cvt_pk_bf16_f32 v129, v10, v11
	v_cvt_pk_bf16_f32 v122, v12, v13
	v_cvt_pk_bf16_f32 v123, v14, v15
	v_cvt_pk_bf16_f32 v124, v16, v17
	v_cvt_pk_bf16_f32 v125, v18, v2
	s_branch .LBB0_687
	s_and_saveexec_b64 s[22:23], s[40:41]
	v_lshl_add_u32 v2, v160, 2, s26
	ds_write_b32 v2, v44 offset:128
	s_or_b64 exec, exec, s[22:23]
	s_waitcnt lgkmcnt(0)
	v_add_u32_e32 v2, s26, v138
	ds_read_b128 v[4:7], v2 offset:224
	ds_read_b128 v[10:13], v2 offset:192
	ds_read_b128 v[24:27], v2 offset:160
	ds_read_b128 v[28:31], v2 offset:128
	s_waitcnt lgkmcnt(0)
	v_pk_mul_f32 v[20:21], v[6:7], 0 op_sel_hi:[1,0]
	v_pk_mul_f32 v[16:17], v[12:13], 0 op_sel_hi:[1,0]
	v_pk_mul_f32 v[12:13], v[26:27], 0 op_sel_hi:[1,0]
	v_pk_mul_f32 v[8:9], v[30:31], 0 op_sel_hi:[1,0]
	v_pk_mul_f32 v[18:19], v[4:5], 0 op_sel_hi:[1,0]
	v_pk_mul_f32 v[14:15], v[10:11], 0 op_sel_hi:[1,0]
	v_pk_mul_f32 v[10:11], v[24:25], 0 op_sel_hi:[1,0]
	v_pk_mul_f32 v[6:7], v[28:29], 0 op_sel_hi:[1,0]
	s_branch .LBB0_688
